# attention item staging: unmasked fast path (twelve ds_writes at precomputed lane addresses) for items whose key rows all exist
# baseline (speedup 1.0000x reference)
.LBB0_330:
	s_load_dwordx2 s[22:23], s[0:1], 0xb8
	s_load_dwordx2 s[24:25], s[0:1], 0xd0
	s_waitcnt vmcnt(0)
	v_xor_b32_e32 v66, 0x80000000, v1
	v_mov_b32_e32 v67, v66
	v_mov_b32_e32 v68, v66
	v_mov_b32_e32 v69, v66
	s_movk_i32 s41, 0x90
	s_mov_b32 s15, 0
	v_mov_b32_e32 v147, 0
	s_movk_i32 s42, 0xffe0
	s_movk_i32 s43, 0x1200
	s_mov_b32 s8, 0x3f803f80
	v_lshrrev_b32_e32 v15, 6, v0
	v_and_b32_e32 v16, 15, v0
	v_bfe_u32 v148, v0, 4, 2
	v_readfirstlane_b32 s92, v15
	v_lshl_or_b32 v17, v15, 5, v16
	v_lshlrev_b32_e32 v146, 2, v148
	v_sub_u32_e32 v14, v16, v146
	v_mov_b32_e32 v15, 0x90
	v_mul_u32_u24_e32 v194, v17, v15
	v_lshl_add_u32 v194, v148, 4, v194
	v_add_u32_e32 v194, 16, v194
	v_lshrrev_b32_e32 v195, 2, v16
	v_add_u32_e32 v195, v195, v146
	v_lshl_add_u32 v195, s92, 5, v195
	v_mul_u32_u24_e32 v195, v195, v15
	v_and_b32_e32 v16, 3, v0
	v_lshl_add_u32 v195, v16, 3, v195
	v_add_u32_e32 v195, 0xd810, v195
	v_cmp_le_i32_e64 s[76:77], v14, 0
	v_cmp_le_i32_e64 s[78:79], v14, 1
	v_cmp_le_i32_e64 s[80:81], v14, 2
	v_cmp_le_i32_e64 s[82:83], v14, 3
	v_cmp_ge_i32_e64 s[84:85], v14, 0
	v_cmp_ge_i32_e64 s[86:87], v14, 1
	v_cmp_ge_i32_e64 s[88:89], v14, 2
	v_cmp_ge_i32_e64 s[90:91], v14, 3
	v_mov_b32_e32 v10, 0x3f803f80
	v_mov_b32_e32 v11, v10
	v_mov_b32_e32 v12, v10
	v_mov_b32_e32 v13, v10
	v_lshrrev_b32_e32 v232, 3, v0
	v_mul_u32_u24_e32 v232, 0x90, v232
	v_and_b32_e32 v233, 7, v0
	v_lshl_add_u32 v232, v233, 4, v232
	v_add_u32_e32 v232, 16, v232
	v_add_u32_e32 v233, 0xd800, v232
	s_branch .LBB0_332

.LBB0_332:
	s_cmp_eq_u32 s17, 0
	s_cbranch_scc0 .Lstg_masked
	ds_write_b128 v232, v[22:25]
	ds_write_b128 v233, v[18:21]
	ds_write_b128 v232, v[30:33] offset:9216
	ds_write_b128 v233, v[26:29] offset:9216
	ds_write_b128 v232, v[38:41] offset:18432
	ds_write_b128 v233, v[34:37] offset:18432
	ds_write_b128 v232, v[46:49] offset:27648
	ds_write_b128 v233, v[42:45] offset:27648
	ds_write_b128 v232, v[54:57] offset:36864
	ds_write_b128 v233, v[50:53] offset:36864
	ds_write_b128 v232, v[62:65] offset:46080
	ds_write_b128 v233, v[58:61] offset:46080
	s_branch .Lstg_done

.LBB0_344:
.Lstg_done:
	s_or_b64 exec, exec, s[6:7]
	v_readlane_b32 s6, v255, 2
	s_add_i32 s40, s40, s6
	s_cmp_ge_i32 s40, s3
	s_cselect_b64 s[26:27], -1, 0
	s_and_b64 vcc, exec, s[26:27]
	s_waitcnt lgkmcnt(0)
	s_barrier
	s_cbranch_vccnz .LBB0_360
	s_and_b64 vcc, exec, s[4:5]
	s_mov_b32 s6, s40
	s_cbranch_vccnz .LBB0_347
	s_mul_hi_i32 s6, s40, 0x2aaaaaab
	s_lshr_b32 s7, s6, 31
	s_ashr_i32 s6, s6, 3
	s_add_i32 s6, s6, s7
	s_lshl_b32 s7, s6, 3
	v_readlane_b32 s9, v255, 3
	s_or_b32 s7, s7, s9
	s_mul_i32 s6, s6, 48
	s_mul_i32 s7, s7, 48
	s_sub_i32 s6, s40, s6
	s_add_i32 s6, s7, s6
